# v054_nocopy
# speedup vs baseline: 1.0061x; 1.0061x over previous
; __device__ __forceinline__ void attn_wave_item(const Params& p, int witem, const int tidx) {
;     ...
;     u32x4 vf[8], kn[8];
;     {
;       const int tn = tile > 0 ? tile - 1 : 0;
;       const char* vp = vbase + (size_t)tile * 8192;
;       const char* kp = kbase + (size_t)tn * 8192;
; #pragma unroll
;       for (int i = 0; i < 8; ++i) vf[i] = *reinterpret_cast<const u32x4*>(vp + i * 1024);
; #pragma unroll
;       for (int ks = 0; ks < 8; ++ks) kn[ks] = *reinterpret_cast<const u32x4*>(kp + ks * 1024);
;     }
;     __builtin_amdgcn_sched_barrier(0);
;     f32x16 S, S2;
; #pragma unroll
;     for (int i = 0; i < 16; ++i) { S[i] = 0.f; S2[i] = 0.f; }
; #pragma unroll
;     for (int ks = 0; ks < 8; ks += 2) {
;       u32x4 qa = *reinterpret_cast<const u32x4*>(qlds + ks * 1024);
;       u32x4 qb = *reinterpret_cast<const u32x4*>(qlds + (ks + 1) * 1024);
;       S = __builtin_amdgcn_mfma_f32_32x32x16_bf16(as_bf16x8(kf[ks]), as_bf16x8(qa), S, 0, 0, 0);
;       S2 = __builtin_amdgcn_mfma_f32_32x32x16_bf16(as_bf16x8(kf[ks + 1]), as_bf16x8(qb), S2, 0, 0, 0);
;     }
; #pragma unroll
;     for (int i = 0; i < 16; ++i) S[i] += S2[i];
;     const bool diag = (tile == qt);
;     float be[16], om[16];
; #pragma unroll
;     for (int r = 0; r < 16; ++r) {
;       float z = S[r];
;       float e = __builtin_amdgcn_exp2f(-fabsf(z));
;       float rr = __builtin_amdgcn_rcpf(1.f + e);
;       float sm = e * rr;
;       int kl = (r & 3) + 8 * (r >> 2) + 4 * half;
;       bool v = !diag || (kl < n);
;       bool pos = z >= 0.f;
;       be[r] = v ? (pos ? rr : sm) : 0.f;
;       om[r] = v ? (pos ? sm : rr) : 1.f;
;     }
;     ...
;     for (int i = 0; i < 8; ++i) kf[i] = kn[i];
.LBB0_119:
	ds_read_b128 v[226:229], v173
	ds_read_b128 v[84:87], v173 offset:1024
	ds_read_b128 v[204:207], v173 offset:2048
	ds_read_b128 v[222:225], v173 offset:3072
	v_sub_u32_e64 v162, v169, 1 clamp
	s_waitcnt vmcnt(0)
	s_cmp_lg_u32 s48, 0
	s_cselect_b64 s[50:51], -1, 0
	s_waitcnt lgkmcnt(3)
	s_setprio 1
	v_mfma_f32_32x32x16_bf16 v[64:79], v[98:101], v[226:229], 0
	s_or_b64 s[44:45], s[6:7], s[50:51]
	s_waitcnt lgkmcnt(2)
	v_mfma_f32_32x32x16_bf16 v[80:95], v[102:105], v[84:87], 0
	s_waitcnt lgkmcnt(1)
	v_mfma_f32_32x32x16_bf16 v[64:79], v[106:109], v[204:207], v[64:79]
	s_waitcnt lgkmcnt(0)
	v_mfma_f32_32x32x16_bf16 v[80:95], v[110:113], v[222:225], v[80:95]
	ds_read_b128 v[196:199], v173 offset:4096
	ds_read_b128 v[200:203], v173 offset:5120
	s_waitcnt lgkmcnt(1)
	v_mfma_f32_32x32x16_bf16 v[64:79], v[114:117], v[196:199], v[64:79]
	s_waitcnt lgkmcnt(0)
	v_mfma_f32_32x32x16_bf16 v[80:95], v[118:121], v[200:203], v[80:95]
	ds_read_b128 v[188:191], v173 offset:6144
	ds_read_b128 v[192:195], v173 offset:7168
	s_waitcnt lgkmcnt(1)
	v_mfma_f32_32x32x16_bf16 v[64:79], v[122:125], v[188:191], v[64:79]
	s_waitcnt lgkmcnt(0)
	v_mfma_f32_32x32x16_bf16 v[80:95], v[126:129], v[192:195], v[80:95]
	s_setprio 0
	v_lshl_add_u64 v[246:247], v[174:175], 0, s[48:49]
	s_mov_b32 s42, 0x20900000
	v_add_co_u32_e64 v248, s[42:43], s42, v246
	s_nop 1
	v_addc_co_u32_e64 v249, s[42:43], 0, v247, s[42:43]
	s_mov_b32 s42, 0x20901000
	v_add_co_u32_e64 v246, s[42:43], s42, v246
	s_nop 1
	v_addc_co_u32_e64 v247, s[42:43], 0, v247, s[42:43]
	global_load_dwordx4 v[154:157], v[248:249], off offset:1024
	global_load_dwordx4 v[150:153], v[248:249], off offset:2048
	global_load_dwordx4 v[142:145], v[248:249], off offset:3072
	global_load_dwordx4 v[158:161], v[246:247], off offset:-4096
	global_load_dwordx4 v[146:149], v[246:247], off
	global_load_dwordx4 v[138:141], v[246:247], off offset:1024
	global_load_dwordx4 v[134:137], v[246:247], off offset:2048
	global_load_dwordx4 v[130:133], v[246:247], off offset:3072
	v_lshlrev_b64 v[250:251], 13, v[162:163]
	v_lshl_add_u64 v[250:251], v[170:171], 0, v[250:251]
	v_add_co_u32_e64 v252, s[42:43], s58, v250
	s_nop 1
	v_addc_co_u32_e64 v253, s[42:43], 0, v251, s[42:43]
	global_load_dwordx4 v[98:101], v[250:251], off
	global_load_dwordx4 v[102:105], v[250:251], off offset:1024
	global_load_dwordx4 v[106:109], v[250:251], off offset:2048
	global_load_dwordx4 v[110:113], v[250:251], off offset:3072
	global_load_dwordx4 v[114:117], v[252:253], off
	global_load_dwordx4 v[118:121], v[252:253], off offset:1024
	global_load_dwordx4 v[122:125], v[252:253], off offset:2048
	global_load_dwordx4 v[126:129], v[252:253], off offset:3072
	s_nop 0
	v_add_f32_e32 v64, v64, v80
	v_exp_f32_e64 v80, -|v64|
	v_add_f32_e32 v65, v65, v81
	v_add_f32_e32 v66, v66, v82
	v_exp_f32_e64 v82, -|v65|
	v_add_f32_e32 v81, 1.0, v80
	v_rcp_f32_e32 v81, v81
	v_add_f32_e32 v67, v67, v83
	v_add_f32_e32 v83, 1.0, v82
	v_cmp_le_f32_e64 s[42:43], 0, v64
	v_mul_f32_e32 v80, v80, v81
	v_rcp_f32_e32 v83, v83
	v_cndmask_b32_e64 v64, v80, v81, s[42:43]
	v_add_f32_e32 v68, v68, v84
	v_cndmask_b32_e64 v84, 0, v64, s[44:45]
	v_cndmask_b32_e64 v64, v81, v80, s[42:43]
	v_exp_f32_e64 v81, -|v66|
	v_cndmask_b32_e64 v80, 1.0, v64, s[44:45]
	v_mul_f32_e32 v64, v82, v83
	v_cmp_le_f32_e64 s[42:43], 0, v65
	s_or_b64 s[44:45], s[8:9], s[50:51]
	v_add_f32_e32 v69, v69, v85
	v_cndmask_b32_e64 v65, v64, v83, s[42:43]
	v_cndmask_b32_e64 v64, v83, v64, s[42:43]
	v_cndmask_b32_e64 v82, 0, v65, s[44:45]
	v_add_f32_e32 v65, 1.0, v81
	v_cndmask_b32_e64 v83, 1.0, v64, s[44:45]
	v_exp_f32_e64 v64, -|v67|
	v_rcp_f32_e32 v65, v65
	v_cmp_le_f32_e64 s[42:43], 0, v66
	s_or_b64 s[44:45], s[10:11], s[50:51]
	v_add_f32_e32 v85, 1.0, v64
	v_mul_f32_e32 v81, v81, v65
	v_rcp_f32_e32 v85, v85
	v_cndmask_b32_e64 v66, v81, v65, s[42:43]
	v_cndmask_b32_e64 v65, v65, v81, s[42:43]
	v_cndmask_b32_e64 v81, 1.0, v65, s[44:45]
	v_exp_f32_e64 v65, -|v68|
	v_mul_f32_e32 v64, v64, v85
	v_cmp_le_f32_e64 s[42:43], 0, v67
	v_exp_f32_e64 v67, -|v69|
	v_add_f32_e32 v70, v70, v86
	v_cndmask_b32_e64 v86, 0, v66, s[44:45]
	v_cndmask_b32_e64 v66, v64, v85, s[42:43]
	s_or_b64 s[44:45], s[12:13], s[50:51]
	v_add_f32_e32 v71, v71, v87
	v_cndmask_b32_e64 v87, 0, v66, s[44:45]
	v_add_f32_e32 v66, 1.0, v65
	v_rcp_f32_e32 v66, v66
	v_cndmask_b32_e64 v64, v85, v64, s[42:43]
	v_cmp_le_f32_e64 s[42:43], 0, v68
	v_add_f32_e32 v68, 1.0, v67
	v_rcp_f32_e32 v68, v68
	v_cndmask_b32_e64 v85, 1.0, v64, s[44:45]
	v_mul_f32_e32 v64, v65, v66
	v_cndmask_b32_e64 v65, v64, v66, s[42:43]
	s_or_b64 s[44:45], s[14:15], s[50:51]
	v_add_f32_e32 v72, v72, v88
	v_cndmask_b32_e64 v88, 0, v65, s[44:45]
	v_mul_f32_e32 v65, v67, v68
	v_exp_f32_e64 v67, -|v70|
	v_cndmask_b32_e64 v64, v66, v64, s[42:43]
	v_cmp_le_f32_e64 s[42:43], 0, v69
	v_cndmask_b32_e64 v64, 1.0, v64, s[44:45]
	s_or_b64 s[44:45], s[16:17], s[50:51]
	v_cndmask_b32_e64 v66, v65, v68, s[42:43]
	v_add_f32_e32 v73, v73, v89
	v_cndmask_b32_e64 v89, 0, v66, s[44:45]
	v_add_f32_e32 v66, 1.0, v67
	v_cndmask_b32_e64 v65, v68, v65, s[42:43]
	v_rcp_f32_e32 v69, v66
	v_cndmask_b32_e64 v66, 1.0, v65, s[44:45]
	v_exp_f32_e64 v65, -|v71|
	v_cmp_le_f32_e64 s[42:43], 0, v70
	v_mul_f32_e32 v67, v67, v69
	s_or_b64 s[44:45], s[18:19], s[50:51]
	v_add_f32_e32 v70, 1.0, v65
	v_rcp_f32_e32 v70, v70
	v_cndmask_b32_e64 v68, v67, v69, s[42:43]
	v_cndmask_b32_e64 v67, v69, v67, s[42:43]
	v_cndmask_b32_e64 v176, 1.0, v67, s[44:45]
	v_exp_f32_e64 v67, -|v72|
	v_mul_f32_e32 v65, v65, v70
	v_cmp_le_f32_e64 s[42:43], 0, v71
	v_add_f32_e32 v74, v74, v90
	v_cndmask_b32_e64 v90, 0, v68, s[44:45]
	v_cndmask_b32_e64 v68, v65, v70, s[42:43]
; __device__ __forceinline__ void attn_wave_item(const Params& p, int witem, const int tidx) {
;     ...
;     for (int r = 0; r < 16; ++r) {
;       float z = S[r];
;       float e = __builtin_amdgcn_exp2f(-fabsf(z));
;       float rr = __builtin_amdgcn_rcpf(1.f + e);
;       float sm = e * rr;
;       int kl = (r & 3) + 8 * (r >> 2) + 4 * half;
;       bool v = !diag || (kl < n);
;       bool pos = z >= 0.f;
;       be[r] = v ? (pos ? rr : sm) : 0.f;
;       om[r] = v ? (pos ? sm : rr) : 1.f;
;     }
;     float gp[4], pgp[4];
; #pragma unroll
;     for (int gi = 0; gi < 4; ++gi) {
;       gp[gi] = (om[4 * gi] * om[4 * gi + 1]) * (om[4 * gi + 2] * om[4 * gi + 3]);
;       pgp[gi] = __shfl_xor(gp[gi], 32, 64);
;     }
;     float w[16];
;     float run = R;
; #pragma unroll
;     ...
;       float a = (half == 0) ? (run * pgp[gi]) : run;
; #pragma unroll
;       for (int r = 3; r >= 0; --r) {
;         int ri = 4 * gi + r;
;         w[ri] = be[ri] * a;
;         a *= om[ri];
;       }
;       run *= gp[gi] * pgp[gi];
;     }
;     R = run;
;     __builtin_amdgcn_sched_barrier(0);
;     bf16x8 pf[2];
; #pragma unroll
;     for (int m = 0; m < 2; ++m) {
;       u32x4 t;
;       t.x = pack2(w[8 * m + 0], w[8 * m + 1]);
;       t.y = pack2(w[8 * m + 2], w[8 * m + 3]);
;       t.z = pack2(w[8 * m + 4], w[8 * m + 5]);
;       t.w = pack2(w[8 * m + 6], w[8 * m + 7]);
;       pf[m] = as_bf16x8(t);
;     }
; #pragma unroll
;     for (int dt = 0; dt < 4; ++dt)
; #pragma unroll
;       for (int m = 0; m < 2; ++m) O[dt] = __builtin_amdgcn_mfma_f32_32x32x16_bf16(as_bf16x8(vf[dt * 2 + m]), pf[m], O[dt], 0, 0, 0);
;     if (__all(R < 1.17549435e-38f)) break;
;     __builtin_amdgcn_sched_barrier(0);
; #pragma unroll
;     for (int i = 0; i < 8; ++i) kf[i] = kn[i];
	s_or_b64 s[44:45], s[20:21], s[50:51]
	v_cndmask_b32_e64 v71, 0, v68, s[44:45]
	v_add_f32_e32 v68, 1.0, v67
	v_cndmask_b32_e64 v65, v70, v65, s[42:43]
	v_rcp_f32_e32 v69, v68
	v_cndmask_b32_e64 v68, 1.0, v65, s[44:45]
	v_exp_f32_e64 v65, -|v73|
	v_cmp_le_f32_e64 s[42:43], 0, v72
	v_mul_f32_e32 v67, v67, v69
	s_or_b64 s[44:45], s[22:23], s[50:51]
	v_add_f32_e32 v72, 1.0, v65
	v_rcp_f32_e32 v72, v72
	v_cndmask_b32_e64 v70, v67, v69, s[42:43]
	v_cndmask_b32_e64 v67, v69, v67, s[42:43]
	v_cmp_le_f32_e64 s[42:43], 0, v73
	v_mul_f32_e32 v65, v65, v72
	v_add_f32_e32 v75, v75, v91
	v_cndmask_b32_e64 v91, 0, v70, s[44:45]
	v_cndmask_b32_e64 v67, 1.0, v67, s[44:45]
	v_exp_f32_e64 v69, -|v74|
	v_cndmask_b32_e64 v70, v65, v72, s[42:43]
	s_or_b64 s[44:45], s[24:25], s[50:51]
	v_cndmask_b32_e64 v65, v72, v65, s[42:43]
	v_add_f32_e32 v77, v77, v93
	v_cndmask_b32_e64 v93, 1.0, v65, s[44:45]
	v_exp_f32_e64 v65, -|v75|
	v_add_f32_e32 v76, v76, v92
	v_cndmask_b32_e64 v92, 0, v70, s[44:45]
	v_add_f32_e32 v70, 1.0, v69
	v_rcp_f32_e32 v70, v70
	v_add_f32_e32 v73, 1.0, v65
	v_rcp_f32_e32 v73, v73
	v_cmp_le_f32_e64 s[42:43], 0, v74
	v_mul_f32_e32 v69, v69, v70
	s_or_b64 s[44:45], s[26:27], s[50:51]
	v_cndmask_b32_e64 v72, v69, v70, s[42:43]
	v_cndmask_b32_e64 v69, v70, v69, s[42:43]
	v_mul_f32_e32 v65, v65, v73
	v_cmp_le_f32_e64 s[42:43], 0, v75
	v_add_f32_e32 v78, v78, v94
	v_add_f32_e32 v79, v79, v95
	v_cndmask_b32_e64 v94, 0, v72, s[44:45]
	v_cndmask_b32_e64 v95, 1.0, v69, s[44:45]
	v_exp_f32_e64 v69, -|v76|
	v_cndmask_b32_e64 v70, v65, v73, s[42:43]
	s_or_b64 s[44:45], s[28:29], s[50:51]
	v_cndmask_b32_e64 v65, v73, v65, s[42:43]
	v_cndmask_b32_e64 v179, 1.0, v65, s[44:45]
	v_exp_f32_e64 v65, -|v77|
	v_cndmask_b32_e64 v162, 0, v70, s[44:45]
	v_add_f32_e32 v70, 1.0, v69
	v_rcp_f32_e32 v70, v70
	v_add_f32_e32 v73, 1.0, v65
	v_rcp_f32_e32 v73, v73
	v_cmp_le_f32_e64 s[42:43], 0, v76
	v_mul_f32_e32 v69, v69, v70
	s_or_b64 s[44:45], s[30:31], s[50:51]
	v_cndmask_b32_e64 v72, v69, v70, s[42:43]
	v_cndmask_b32_e64 v69, v70, v69, s[42:43]
	v_mul_f32_e32 v65, v65, v73
	v_cmp_le_f32_e64 s[42:43], 0, v77
	v_cndmask_b32_e64 v74, 0, v72, s[44:45]
	v_cndmask_b32_e64 v69, 1.0, v69, s[44:45]
	v_exp_f32_e64 v70, -|v78|
	v_cndmask_b32_e64 v72, v65, v73, s[42:43]
	s_or_b64 s[44:45], s[34:35], s[50:51]
	v_cndmask_b32_e64 v65, v73, v65, s[42:43]
	v_cndmask_b32_e64 v73, 1.0, v65, s[44:45]
	v_exp_f32_e64 v65, -|v79|
	v_cndmask_b32_e64 v75, 0, v72, s[44:45]
	v_add_f32_e32 v72, 1.0, v70
	v_rcp_f32_e32 v72, v72
	v_add_f32_e32 v77, 1.0, v65
	v_rcp_f32_e32 v77, v77
	v_cmp_le_f32_e64 s[42:43], 0, v78
	v_mul_f32_e32 v70, v70, v72
	s_or_b64 s[44:45], s[36:37], s[50:51]
	v_cndmask_b32_e64 v76, v70, v72, s[42:43]
	v_cndmask_b32_e64 v70, v72, v70, s[42:43]
	v_mul_f32_e32 v65, v65, v77
	v_cmp_le_f32_e64 s[42:43], 0, v79
	v_cndmask_b32_e64 v76, 0, v76, s[44:45]
	v_cndmask_b32_e64 v78, 1.0, v70, s[44:45]
	v_cndmask_b32_e64 v70, v65, v77, s[42:43]
	s_or_b64 s[44:45], s[38:39], s[50:51]
	v_cndmask_b32_e64 v65, v77, v65, s[42:43]
	v_cndmask_b32_e64 v77, 1.0, v65, s[44:45]
	v_mul_f32_e32 v65, v69, v73
	v_mul_f32_e32 v69, v78, v77
	v_mul_f32_e32 v69, v65, v69
	v_cndmask_b32_e64 v79, 0, v70, s[44:45]
	v_mul_f32_e32 v70, v80, v83
	ds_bpermute_b32 v80, v178, v69
	v_mul_f32_e32 v65, v67, v93
	v_mul_f32_e32 v67, v95, v179
	v_mul_f32_e32 v65, v65, v67
	ds_bpermute_b32 v67, v178, v65
	s_waitcnt lgkmcnt(1)
	v_mul_f32_e32 v180, v177, v80
	v_cndmask_b32_e32 v180, v177, v180, vcc
	v_mul_f32_e32 v77, v180, v77
	v_mul_f32_e32 v76, v76, v77
	v_mul_f32_e32 v77, v78, v77
	v_mul_f32_e32 v73, v73, v77
	v_mul_f32_e32 v69, v69, v80
	v_mul_f32_e32 v78, v75, v77
	v_mul_f32_e32 v77, v74, v73
	v_pk_mul_f32 v[74:75], v[176:177], v[68:69]
	s_waitcnt lgkmcnt(0)
	v_pk_mul_f32 v[64:65], v[64:65], v[66:67]
	v_mul_f32_e32 v67, v75, v67
	v_pk_mul_f32 v[64:65], v[64:65], v[74:75]
	ds_bpermute_b32 v73, v178, v64
	v_cndmask_b32_e32 v67, v75, v67, vcc
	v_mul_f32_e32 v74, v162, v67
	v_mul_f32_e32 v67, v179, v67
	v_mul_f32_e32 v75, v94, v67
	v_mul_f32_e32 v67, v95, v67
	v_mul_f32_e32 v80, v92, v67
	v_mul_f32_e32 v67, v93, v67
	v_mul_f32_e32 v91, v91, v67
	s_waitcnt lgkmcnt(0)
	v_mul_f32_e32 v67, v65, v73
	v_cndmask_b32_e32 v67, v65, v67, vcc
	v_mul_f32_e32 v72, v81, v85
	v_mul_f32_e32 v92, v71, v67
	v_mov_b32_e32 v71, v64
	v_mul_f32_e32 v67, v68, v67
	v_pk_mul_f32 v[68:69], v[70:71], v[72:73]
	ds_bpermute_b32 v64, v178, v68
	v_mul_f32_e32 v90, v90, v67
	v_mul_f32_e32 v67, v176, v67
	v_mul_f32_e32 v70, v89, v67
	v_mul_f32_e32 v66, v66, v67
	s_waitcnt lgkmcnt(0)
	v_pk_mul_f32 v[72:73], v[68:69], v[64:65]
	v_mul_f32_e32 v79, v180, v79
	v_mul_f32_e32 v64, v73, v64
	v_cndmask_b32_e32 v64, v73, v64, vcc
	v_mul_f32_e32 v65, v87, v64
	v_mul_f32_e32 v64, v85, v64
	v_mul_f32_e32 v67, v86, v64
	v_mul_f32_e32 v64, v81, v64
	v_mul_f32_e32 v68, v82, v64
	v_mul_f32_e32 v64, v83, v64
	v_mul_f32_e32 v66, v88, v66
	v_mul_f32_e32 v64, v84, v64
	v_cvt_pk_bf16_f32 v64, v64, v68
	v_cvt_pk_bf16_f32 v65, v67, v65
	v_cvt_pk_bf16_f32 v66, v66, v70
	v_cvt_pk_bf16_f32 v67, v90, v92
	v_cvt_pk_bf16_f32 v68, v91, v80
	v_cvt_pk_bf16_f32 v69, v75, v74
	v_cvt_pk_bf16_f32 v70, v77, v78
	v_cvt_pk_bf16_f32 v71, v76, v79
	v_mul_f32_e32 v177, v72, v73
	s_waitcnt vmcnt(12)
	s_setprio 1
	v_mfma_f32_32x32x16_bf16 v[48:63], v[158:161], v[64:67], v[48:63]
	v_cmp_gt_f32_e64 s[42:43], s1, v177
	s_or_b64 s[92:93], s[92:93], exec
	s_mov_b64 s[44:45], -1
	s_cmp_lg_u64 s[42:43], exec
	v_mfma_f32_32x32x16_bf16 v[32:47], v[150:153], v[64:67], v[32:47]
	s_waitcnt vmcnt(11)
	v_mfma_f32_32x32x16_bf16 v[16:31], v[146:149], v[64:67], v[16:31]
	s_waitcnt vmcnt(9)
	v_mfma_f32_32x32x16_bf16 v[0:15], v[134:137], v[64:67], v[0:15]
	v_mfma_f32_32x32x16_bf16 v[48:63], v[154:157], v[68:71], v[48:63]
	v_mfma_f32_32x32x16_bf16 v[32:47], v[142:145], v[68:71], v[32:47]
	v_mfma_f32_32x32x16_bf16 v[16:31], v[138:141], v[68:71], v[16:31]
	s_waitcnt vmcnt(8)
	v_mfma_f32_32x32x16_bf16 v[0:15], v[130:133], v[68:71], v[0:15]
	s_setprio 0
	s_cbranch_scc1 .LBB0_117
	s_branch .LBB0_118
